# same as previous best plus the two wait states the compiler keeps between a VALU carry-out and its carry-in, added at the hand-written address computations
# speedup vs baseline: 1.0112x; 1.0001x over previous
.LBB0_621:
	s_or_b64 exec, exec, s[30:31]
	s_waitcnt lgkmcnt(0)
	s_barrier
	s_and_saveexec_b64 s[30:31], s[24:25]
	s_cbranch_execz .LBB0_634
	v_readlane_b32 s4, v242, 22
	v_readlane_b32 s5, v242, 23
	s_lshl_b64 s[4:5], s[4:5], 2
	v_readlane_b32 s50, v242, 24
	s_add_u32 s4, s62, s4
	v_readlane_b32 s51, v242, 25
	s_addc_u32 s5, s63, s5
	s_lshl_b64 s[50:51], s[50:51], 2
	s_add_u32 s40, s40, s50
	s_addc_u32 s41, s41, s51
	s_lshl_b32 s38, s55, 7
	v_or_b32_e32 v46, s38, v69
	v_add_u32_e32 v2, s38, v144
	v_cndmask_b32_e64 v2, v2, v46, s[22:23]
	v_lshlrev_b32_e32 v24, 2, v2
	v_mov_b32_e32 v25, v11
	v_lshl_add_u64 v[28:29], s[4:5], 0, v[24:25]
	global_load_dwordx4 v[2:5], v24, s[40:41] offset:16
	global_load_dwordx4 v[6:9], v24, s[40:41]
	global_load_dwordx4 v[12:15], v24, s[4:5] offset:16
	global_load_dwordx4 v[16:19], v24, s[4:5]
	global_load_dwordx4 v[20:23], v24, s[4:5] offset:3088
	s_nop 0
	global_load_dwordx4 v[24:27], v24, s[4:5] offset:3072
	s_movk_i32 s4, 0x1000
	v_add_co_u32_e32 v30, vcc, s4, v28
	s_mov_b64 s[50:51], 0x1800
	s_nop 0
	v_addc_co_u32_e32 v31, vcc, 0, v29, vcc
	s_movk_i32 s4, 0x2000
	v_lshl_add_u64 v[36:37], v[28:29], 0, s[50:51]
	s_mov_b64 s[50:51], 0x2400
	v_add_co_u32_e32 v32, vcc, s4, v28
	v_lshl_add_u64 v[40:41], v[28:29], 0, s[50:51]
	s_nop 0
	v_addc_co_u32_e32 v33, vcc, 0, v29, vcc
	global_load_dwordx4 v[28:31], v[30:31], off offset:2048
	s_nop 0
	global_load_dwordx4 v[32:35], v[32:33], off offset:1024
	s_nop 0
	global_load_dwordx4 v[36:39], v[36:37], off offset:16
	s_nop 0
	global_load_dwordx4 v[40:43], v[40:41], off offset:16
	s_lshl_b32 s4, s96, 7
	s_lshr_b32 s40, s47, 7
	s_mov_b32 s41, s49
	s_and_b32 s4, s4, 0x3f00
	s_lshl_b64 s[40:41], s[40:41], 14
	v_or_b32_e32 v46, 0x800, v46
	v_add_u32_e32 v47, s38, v146
	s_or_b32 s40, s40, s4
	v_cndmask_b32_e64 v46, v47, v46, s[22:23]
	ds_read_b32 v54, v145 offset:1020
	v_lshl_add_u64 v[44:45], s[40:41], 0, v[70:71]
	v_lshlrev_b32_e32 v46, 1, v46
	v_mov_b32_e32 v47, v11
	v_mad_u64_u32 v[46:47], s[40:41], v44, s64, v[46:47]
	v_mad_i32_i24 v47, v45, s64, v47
	v_lshl_add_u64 v[44:45], s[34:35], 0, v[46:47]
	s_mov_b64 s[40:41], 0x97fb800
	v_lshl_add_u64 v[44:45], v[44:45], 0, s[40:41]
	s_mov_b64 s[40:41], 0
	v_mov_b32_e32 v55, v158
	v_mov_b32_e32 v56, v157
	v_mov_b32_e32 v57, v70
	s_add_u32 s98, s94, 0x1000
	s_addc_u32 s99, s95, 0
	v_mov_b32_e32 v236, 0x3000
	v_mov_b32_e32 v237, 0
	v_add_co_u32_e32 v198, vcc, 0x1000, v44
	s_nop 1
	v_addc_co_u32_e32 v199, vcc, 0, v45, vcc
	v_add_co_u32_e32 v200, vcc, 0x4000, v44
	s_nop 1
	v_addc_co_u32_e32 v201, vcc, 0, v45, vcc
	global_load_dwordx4 v[214:217], v[198:199], off offset:-4096
	global_load_dwordx4 v[218:221], v[198:199], off offset:2048
	global_load_dwordx4 v[222:225], v[200:201], off offset:-4096
	global_load_dwordx4 v[226:229], v[200:201], off offset:2048
	s_branch .LBB0_624

.LBB0_1424:
	v_mov_b32_e32 v47, 0
	s_andn2_b64 vcc, exec, s[8:9]
	v_mov_b32_e32 v46, v47
	v_mov_b32_e32 v45, v47
	v_mov_b32_e32 v44, v47
	v_mov_b32_e32 v51, v47
	v_mov_b32_e32 v50, v47
	v_mov_b32_e32 v49, v47
	v_mov_b32_e32 v48, v47
	s_waitcnt vmcnt(0)
	v_mov_b32_e32 v55, v47
	v_mov_b32_e32 v54, v47
	v_mov_b32_e32 v53, v47
	v_mov_b32_e32 v52, v47
	v_mov_b32_e32 v59, v47
	v_mov_b32_e32 v58, v47
	v_mov_b32_e32 v57, v47
	v_mov_b32_e32 v56, v47
	v_mov_b32_e32 v63, v47
	v_mov_b32_e32 v62, v47
	v_mov_b32_e32 v61, v47
	v_mov_b32_e32 v60, v47
	v_mov_b32_e32 v67, v47
	v_mov_b32_e32 v66, v47
	v_mov_b32_e32 v65, v47
	v_mov_b32_e32 v64, v47
	v_mov_b32_e32 v71, v47
	v_mov_b32_e32 v70, v47
	v_mov_b32_e32 v69, v47
	v_mov_b32_e32 v68, v47
	v_mov_b32_e32 v75, v47
	v_mov_b32_e32 v74, v47
	v_mov_b32_e32 v73, v47
	v_mov_b32_e32 v72, v47
	v_mov_b32_e32 v79, v47
	v_mov_b32_e32 v78, v47
	v_mov_b32_e32 v77, v47
	v_mov_b32_e32 v76, v47
	v_mov_b32_e32 v83, v47
	v_mov_b32_e32 v82, v47
	v_mov_b32_e32 v81, v47
	v_mov_b32_e32 v80, v47
	v_mov_b32_e32 v87, v47
	v_mov_b32_e32 v86, v47
	v_mov_b32_e32 v85, v47
	v_mov_b32_e32 v84, v47
	v_mov_b32_e32 v91, v47
	v_mov_b32_e32 v90, v47
	v_mov_b32_e32 v89, v47
	v_mov_b32_e32 v88, v47
	v_mov_b32_e32 v95, v47
	v_mov_b32_e32 v94, v47
	v_mov_b32_e32 v93, v47
	v_mov_b32_e32 v92, v47
	v_mov_b32_e32 v103, v47
	v_mov_b32_e32 v102, v47
	v_mov_b32_e32 v101, v47
	v_mov_b32_e32 v100, v47
	v_mov_b32_e32 v107, v47
	v_mov_b32_e32 v106, v47
	v_mov_b32_e32 v105, v47
	v_mov_b32_e32 v104, v47
	v_mov_b32_e32 v99, v47
	v_mov_b32_e32 v98, v47
	v_mov_b32_e32 v97, v47
	v_mov_b32_e32 v96, v47
	s_cbranch_vccnz .LBB0_1509
	v_log_f32_e32 v3, v3
	v_log_f32_e32 v2, v2
	v_log_f32_e32 v5, v5
	v_log_f32_e32 v4, v4
	s_add_i32 s10, s97, 0xfffffdf1
	s_not_b32 s6, s12
	v_readlane_b32 s4, v243, 60
	v_add_f32_e32 v168, v3, v113
	v_add_f32_e32 v169, v2, v114
	v_lshl_add_u32 v2, v110, 10, s18
	v_lshlrev_b32_e32 v3, 2, v10
	s_add_u32 s4, s90, s4
	v_add3_u32 v170, v2, v3, 0
	v_lshlrev_b32_e32 v2, 6, v10
	s_addc_u32 s5, s91, 0
	v_mov_b32_e32 v96, 0
	v_add_f32_e32 v166, v5, v111
	v_add_f32_e32 v167, v4, v112
	v_mov_b32_e32 v156, v148
	v_mov_b32_e32 v157, v148
	v_mov_b32_e32 v158, v152
	v_mov_b32_e32 v159, v152
	v_mov_b32_e32 v160, v150
	v_mov_b32_e32 v161, v150
	v_mov_b32_e32 v162, v154
	v_mov_b32_e32 v163, v154
	v_sub_u32_e32 v171, v110, v2
	v_lshl_add_u64 v[164:165], v[108:109], 1, s[4:5]
	v_mov_b32_e32 v172, s6
	v_mov_b32_e32 v97, v96
	v_mov_b32_e32 v98, v96
	v_mov_b32_e32 v99, v96
	v_mov_b32_e32 v104, v96
	v_mov_b32_e32 v105, v96
	v_mov_b32_e32 v106, v96
	v_mov_b32_e32 v107, v96
	v_mov_b32_e32 v100, v96
	v_mov_b32_e32 v101, v96
	v_mov_b32_e32 v102, v96
	v_mov_b32_e32 v103, v96
	v_mov_b32_e32 v92, v96
	v_mov_b32_e32 v93, v96
	v_mov_b32_e32 v94, v96
	v_mov_b32_e32 v95, v96
	v_mov_b32_e32 v88, v96
	v_mov_b32_e32 v89, v96
	v_mov_b32_e32 v90, v96
	v_mov_b32_e32 v91, v96
	v_mov_b32_e32 v84, v96
	v_mov_b32_e32 v85, v96
	v_mov_b32_e32 v86, v96
	v_mov_b32_e32 v87, v96
	v_mov_b32_e32 v80, v96
	v_mov_b32_e32 v81, v96
	v_mov_b32_e32 v82, v96
	v_mov_b32_e32 v83, v96
	v_mov_b32_e32 v76, v96
	v_mov_b32_e32 v77, v96
	v_mov_b32_e32 v78, v96
	v_mov_b32_e32 v79, v96
	v_mov_b32_e32 v72, v96
	v_mov_b32_e32 v73, v96
	v_mov_b32_e32 v74, v96
	v_mov_b32_e32 v75, v96
	v_mov_b32_e32 v68, v96
	v_mov_b32_e32 v69, v96
	v_mov_b32_e32 v70, v96
	v_mov_b32_e32 v71, v96
	v_mov_b32_e32 v64, v96
	v_mov_b32_e32 v65, v96
	v_mov_b32_e32 v66, v96
	v_mov_b32_e32 v67, v96
	v_mov_b32_e32 v60, v96
	v_mov_b32_e32 v61, v96
	v_mov_b32_e32 v62, v96
	v_mov_b32_e32 v63, v96
	v_mov_b32_e32 v56, v96
	v_mov_b32_e32 v57, v96
	v_mov_b32_e32 v58, v96
	v_mov_b32_e32 v59, v96
	v_mov_b32_e32 v52, v96
	v_mov_b32_e32 v53, v96
	v_mov_b32_e32 v54, v96
	v_mov_b32_e32 v55, v96
	v_mov_b32_e32 v48, v96
	v_mov_b32_e32 v49, v96
	v_mov_b32_e32 v50, v96
	v_mov_b32_e32 v51, v96
	v_mov_b32_e32 v44, v96
	v_mov_b32_e32 v45, v96
	v_mov_b32_e32 v46, v96
	v_mov_b32_e32 v47, v96
	v_add_co_u32_e32 v6, vcc, s80, v164
	s_nop 1
	v_addc_co_u32_e32 v7, vcc, -1, v165, vcc
	global_load_dwordx4 v[196:199], v[6:7], off offset:-3072
	global_load_dwordx4 v[214:217], v[6:7], off offset:-1024
	global_load_dwordx4 v[224:227], v[6:7], off offset:-2048
	global_load_dwordx4 v[228:231], v[6:7], off offset:0
	global_load_dwordx4 v[244:247], v[164:165], off offset:-3072
	global_load_dwordx4 v[248:251], v[164:165], off offset:-2048
	global_load_dwordx4 v[252:255], v[164:165], off offset:-1024
	global_load_dwordx2 v[218:219], v[164:165], off offset:0
	global_load_dword v220, v[164:165], off offset:8
	global_load_dword v223, v[164:165], off offset:12
	v_lshl_add_u64 v[164:165], v[164:165], 0, s[58:59]
	s_branch .LBB0_1427

.LBB0_1924:
	v_mov_b32_e32 v47, 0
	s_andn2_b64 vcc, exec, s[14:15]
	v_mov_b32_e32 v46, v47
	v_mov_b32_e32 v45, v47
	v_mov_b32_e32 v44, v47
	v_mov_b32_e32 v51, v47
	v_mov_b32_e32 v50, v47
	v_mov_b32_e32 v49, v47
	v_mov_b32_e32 v48, v47
	s_waitcnt vmcnt(0)
	v_mov_b32_e32 v55, v47
	v_mov_b32_e32 v54, v47
	v_mov_b32_e32 v53, v47
	v_mov_b32_e32 v52, v47
	v_mov_b32_e32 v59, v47
	v_mov_b32_e32 v58, v47
	v_mov_b32_e32 v57, v47
	v_mov_b32_e32 v56, v47
	v_mov_b32_e32 v63, v47
	v_mov_b32_e32 v62, v47
	v_mov_b32_e32 v61, v47
	v_mov_b32_e32 v60, v47
	v_mov_b32_e32 v67, v47
	v_mov_b32_e32 v66, v47
	v_mov_b32_e32 v65, v47
	v_mov_b32_e32 v64, v47
	v_mov_b32_e32 v71, v47
	v_mov_b32_e32 v70, v47
	v_mov_b32_e32 v69, v47
	v_mov_b32_e32 v68, v47
	v_mov_b32_e32 v75, v47
	v_mov_b32_e32 v74, v47
	v_mov_b32_e32 v73, v47
	v_mov_b32_e32 v72, v47
	v_mov_b32_e32 v79, v47
	v_mov_b32_e32 v78, v47
	v_mov_b32_e32 v77, v47
	v_mov_b32_e32 v76, v47
	v_mov_b32_e32 v83, v47
	v_mov_b32_e32 v82, v47
	v_mov_b32_e32 v81, v47
	v_mov_b32_e32 v80, v47
	v_mov_b32_e32 v87, v47
	v_mov_b32_e32 v86, v47
	v_mov_b32_e32 v85, v47
	v_mov_b32_e32 v84, v47
	v_mov_b32_e32 v91, v47
	v_mov_b32_e32 v90, v47
	v_mov_b32_e32 v89, v47
	v_mov_b32_e32 v88, v47
	v_mov_b32_e32 v95, v47
	v_mov_b32_e32 v94, v47
	v_mov_b32_e32 v93, v47
	v_mov_b32_e32 v92, v47
	v_mov_b32_e32 v103, v47
	v_mov_b32_e32 v102, v47
	v_mov_b32_e32 v101, v47
	v_mov_b32_e32 v100, v47
	v_mov_b32_e32 v107, v47
	v_mov_b32_e32 v106, v47
	v_mov_b32_e32 v105, v47
	v_mov_b32_e32 v104, v47
	v_mov_b32_e32 v99, v47
	v_mov_b32_e32 v98, v47
	v_mov_b32_e32 v97, v47
	v_mov_b32_e32 v96, v47
	s_cbranch_vccnz .LBB0_2009
	v_log_f32_e32 v3, v3
	v_log_f32_e32 v2, v2
	v_log_f32_e32 v5, v5
	v_log_f32_e32 v4, v4
	s_add_i32 s23, s35, 0x3d71
	s_not_b32 s12, s21
	v_readlane_b32 s4, v243, 60
	v_add_f32_e32 v168, v3, v113
	v_add_f32_e32 v169, v2, v114
	v_lshl_add_u32 v2, v110, 10, s29
	v_lshlrev_b32_e32 v3, 2, v10
	s_add_u32 s4, s16, s4
	v_add3_u32 v170, v2, v3, 0
	v_lshlrev_b32_e32 v2, 6, v10
	s_addc_u32 s5, s17, 0
	v_mov_b32_e32 v96, 0
	v_add_f32_e32 v166, v5, v111
	v_add_f32_e32 v167, v4, v112
	v_mov_b32_e32 v156, v148
	v_mov_b32_e32 v157, v148
	v_mov_b32_e32 v158, v152
	v_mov_b32_e32 v159, v152
	v_mov_b32_e32 v160, v150
	v_mov_b32_e32 v161, v150
	v_mov_b32_e32 v162, v154
	v_mov_b32_e32 v163, v154
	v_sub_u32_e32 v171, v110, v2
	v_lshl_add_u64 v[164:165], v[108:109], 1, s[4:5]
	v_mov_b32_e32 v172, s12
	v_mov_b32_e32 v97, v96
	v_mov_b32_e32 v98, v96
	v_mov_b32_e32 v99, v96
	v_mov_b32_e32 v104, v96
	v_mov_b32_e32 v105, v96
	v_mov_b32_e32 v106, v96
	v_mov_b32_e32 v107, v96
	v_mov_b32_e32 v100, v96
	v_mov_b32_e32 v101, v96
	v_mov_b32_e32 v102, v96
	v_mov_b32_e32 v103, v96
	v_mov_b32_e32 v92, v96
	v_mov_b32_e32 v93, v96
	v_mov_b32_e32 v94, v96
	v_mov_b32_e32 v95, v96
	v_mov_b32_e32 v88, v96
	v_mov_b32_e32 v89, v96
	v_mov_b32_e32 v90, v96
	v_mov_b32_e32 v91, v96
	v_mov_b32_e32 v84, v96
	v_mov_b32_e32 v85, v96
	v_mov_b32_e32 v86, v96
	v_mov_b32_e32 v87, v96
	v_mov_b32_e32 v80, v96
	v_mov_b32_e32 v81, v96
	v_mov_b32_e32 v82, v96
	v_mov_b32_e32 v83, v96
	v_mov_b32_e32 v76, v96
	v_mov_b32_e32 v77, v96
	v_mov_b32_e32 v78, v96
	v_mov_b32_e32 v79, v96
	v_mov_b32_e32 v72, v96
	v_mov_b32_e32 v73, v96
	v_mov_b32_e32 v74, v96
	v_mov_b32_e32 v75, v96
	v_mov_b32_e32 v68, v96
	v_mov_b32_e32 v69, v96
	v_mov_b32_e32 v70, v96
	v_mov_b32_e32 v71, v96
	v_mov_b32_e32 v64, v96
	v_mov_b32_e32 v65, v96
	v_mov_b32_e32 v66, v96
	v_mov_b32_e32 v67, v96
	v_mov_b32_e32 v60, v96
	v_mov_b32_e32 v61, v96
	v_mov_b32_e32 v62, v96
	v_mov_b32_e32 v63, v96
	v_mov_b32_e32 v56, v96
	v_mov_b32_e32 v57, v96
	v_mov_b32_e32 v58, v96
	v_mov_b32_e32 v59, v96
	v_mov_b32_e32 v52, v96
	v_mov_b32_e32 v53, v96
	v_mov_b32_e32 v54, v96
	v_mov_b32_e32 v55, v96
	v_mov_b32_e32 v48, v96
	v_mov_b32_e32 v49, v96
	v_mov_b32_e32 v50, v96
	v_mov_b32_e32 v51, v96
	v_mov_b32_e32 v44, v96
	v_mov_b32_e32 v45, v96
	v_mov_b32_e32 v46, v96
	v_mov_b32_e32 v47, v96
	v_add_co_u32_e32 v6, vcc, s80, v164
	s_nop 1
	v_addc_co_u32_e32 v7, vcc, -1, v165, vcc
	global_load_dwordx4 v[196:199], v[6:7], off offset:-3072
	global_load_dwordx4 v[232:235], v[6:7], off offset:-1024
	global_load_dwordx4 v[244:247], v[6:7], off offset:-2048
	global_load_dwordx4 v[248:251], v[6:7], off offset:0
	global_load_dwordx4 v[252:255], v[164:165], off offset:-3072
	global_load_dwordx2 v[228:229], v[164:165], off offset:-2048
	global_load_dwordx2 v[236:237], v[164:165], off offset:-2040
	global_load_dword v195, v[164:165], off offset:-1024
	global_load_dword v200, v[164:165], off offset:-1020
	global_load_dword v203, v[164:165], off offset:-1016
	global_load_dword v221, v[164:165], off offset:-1012
	global_load_dword v222, v[164:165], off offset:0
	global_load_dword v231, v[164:165], off offset:4
	global_load_dword v239, v[164:165], off offset:8
	global_load_dword v240, v[164:165], off offset:12
	v_lshl_add_u64 v[164:165], v[164:165], 0, s[58:59]
	s_branch .LBB0_1927

.LBB0_2269:
	s_or_b64 exec, exec, s[30:31]
	v_cndmask_b32_e64 v2, 0, 1, s[34:35]
	s_lshr_b32 s4, s2, 1
	v_lshlrev_b32_e32 v58, 8, v2
	v_or_b32_e32 v2, s96, v129
	s_and_b32 s4, s4, 63
	v_lshlrev_b32_e32 v10, 2, v2
	s_lshl_b32 s30, s4, 8
	v_lshl_add_u64 v[46:47], s[28:29], 0, v[10:11]
	v_lshl_add_u64 v[44:45], s[26:27], 0, v[10:11]
	s_waitcnt lgkmcnt(0)
	s_barrier
	s_and_saveexec_b64 s[16:17], s[8:9]
	s_cbranch_execz .LBB0_2280
	s_mov_b64 s[4:5], 0x400
	v_lshl_add_u64 v[24:25], v[44:45], 0, s[4:5]
	s_mov_b64 s[4:5], 0x1c00
	v_lshl_add_u64 v[36:37], v[44:45], 0, s[4:5]
	s_mov_b64 s[4:5], 0x2800
	v_lshl_add_u64 v[40:41], v[44:45], 0, s[4:5]
	s_movk_i32 s4, 0x1000
	v_add_co_u32_e32 v28, vcc, s4, v44
	s_movk_i32 s4, 0x2000
	s_nop 0
	v_addc_co_u32_e32 v29, vcc, 0, v45, vcc
	global_load_dwordx4 v[2:5], v[46:47], off offset:1040
	global_load_dwordx4 v[6:9], v[46:47], off offset:1024
	global_load_dwordx4 v[12:15], v[44:45], off offset:1040
	global_load_dwordx4 v[16:19], v[44:45], off offset:1024
	global_load_dwordx4 v[20:23], v[24:25], off offset:3088
	s_nop 0
	global_load_dwordx4 v[24:27], v[24:25], off offset:3072
	v_add_co_u32_e32 v32, vcc, s4, v44
	s_add_u32 s4, s30, s24
	s_nop 0
	v_addc_co_u32_e32 v33, vcc, 0, v45, vcc
	global_load_dwordx4 v[28:31], v[28:29], off offset:3072
	s_nop 0
	global_load_dwordx4 v[32:35], v[32:33], off offset:2048
	s_nop 0
	global_load_dwordx4 v[36:39], v[36:37], off offset:16
	s_nop 0
	global_load_dwordx4 v[40:43], v[40:41], off offset:16
	s_addc_u32 s5, 0, s25
	v_lshl_add_u64 v[50:51], s[4:5], 0, v[68:69]
	v_mad_u64_u32 v[52:53], s[4:5], v50, s64, 0
	v_lshl_add_u64 v[48:49], s[90:91], 0, v[72:73]
	v_mad_i32_i24 v51, v51, s64, v53
	v_or_b32_e32 v50, v52, v58
	v_lshl_add_u64 v[48:49], v[48:49], 0, v[50:51]
	s_mov_b64 s[4:5], 0x97fca00
	v_lshl_add_u64 v[48:49], v[48:49], 0, s[4:5]
	s_mov_b64 s[26:27], 0
	v_mov_b32_e32 v10, v136
	v_mov_b32_e32 v59, v68
	s_add_u32 s50, s60, 0x1000
	s_addc_u32 s51, s61, 0
	s_add_u32 s98, s60, 0x4000
	s_addc_u32 s99, s61, 0
	v_add_co_u32_e32 v198, vcc, 0x1000, v48
	s_nop 1
	v_addc_co_u32_e32 v199, vcc, 0, v49, vcc
	v_add_co_u32_e32 v200, vcc, 0x4000, v48
	s_nop 1
	v_addc_co_u32_e32 v201, vcc, 0, v49, vcc
	global_load_dwordx4 v[150:153], v[198:199], off offset:-4096
	global_load_dwordx4 v[154:157], v[198:199], off offset:2048
	global_load_dwordx4 v[158:161], v[200:201], off offset:-4096
	global_load_dwordx4 v[162:165], v[200:201], off offset:2048
	s_branch .LBB0_2272

.LBB0_2280:
	s_waitcnt vmcnt(0)
	s_or_b64 exec, exec, s[16:17]
	s_and_saveexec_b64 s[16:17], s[8:9]
	s_cbranch_execz .LBB0_2291
	s_mov_b64 s[4:5], 0x1800
	s_waitcnt vmcnt(1)
	v_lshl_add_u64 v[36:37], v[44:45], 0, s[4:5]
	s_mov_b64 s[4:5], 0x2400
	s_waitcnt vmcnt(0)
	v_lshl_add_u64 v[40:41], v[44:45], 0, s[4:5]
	s_movk_i32 s4, 0x1000
	v_add_co_u32_e32 v28, vcc, s4, v44
	s_movk_i32 s4, 0x2000
	s_nop 0
	v_addc_co_u32_e32 v29, vcc, 0, v45, vcc
	global_load_dwordx4 v[2:5], v[46:47], off offset:16
	global_load_dwordx4 v[6:9], v[46:47], off
	global_load_dwordx4 v[12:15], v[44:45], off offset:16
	global_load_dwordx4 v[16:19], v[44:45], off
	global_load_dwordx4 v[20:23], v[44:45], off offset:3088
	global_load_dwordx4 v[24:27], v[44:45], off offset:3072
	v_add_co_u32_e32 v32, vcc, s4, v44
	s_add_u32 s4, s30, s24
	s_nop 0
	v_addc_co_u32_e32 v33, vcc, 0, v45, vcc
	global_load_dwordx4 v[28:31], v[28:29], off offset:2048
	s_nop 0
	global_load_dwordx4 v[32:35], v[32:33], off offset:1024
	s_nop 0
	global_load_dwordx4 v[36:39], v[36:37], off offset:16
	s_nop 0
	global_load_dwordx4 v[40:43], v[40:41], off offset:16
	s_addc_u32 s5, 0, s25
	v_lshl_add_u64 v[46:47], s[4:5], 0, v[68:69]
	v_mad_u64_u32 v[48:49], s[4:5], v46, s64, 0
	v_lshl_add_u64 v[44:45], s[90:91], 0, v[72:73]
	v_mad_i32_i24 v47, v47, s64, v49
	v_or_b32_e32 v46, v48, v58
	v_lshl_add_u64 v[44:45], v[44:45], 0, v[46:47]
	s_mov_b64 s[4:5], 0x97fc800
	v_lshl_add_u64 v[44:45], v[44:45], 0, s[4:5]
	s_mov_b64 s[24:25], 0
	v_mov_b32_e32 v10, v138
	v_mov_b32_e32 v54, v137
	v_mov_b32_e32 v55, v68
	s_add_u32 s50, s60, 0x1000
	s_addc_u32 s51, s61, 0
	s_add_u32 s98, s60, 0x4000
	s_addc_u32 s99, s61, 0
	v_add_co_u32_e32 v198, vcc, 0x1000, v44
	s_nop 1
	v_addc_co_u32_e32 v199, vcc, 0, v45, vcc
	v_add_co_u32_e32 v200, vcc, 0x4000, v44
	s_nop 1
	v_addc_co_u32_e32 v201, vcc, 0, v45, vcc
	global_load_dwordx4 v[150:153], v[198:199], off offset:-4096
	global_load_dwordx4 v[154:157], v[198:199], off offset:2048
	global_load_dwordx4 v[158:161], v[200:201], off offset:-4096
	global_load_dwordx4 v[162:165], v[200:201], off offset:2048
	s_branch .LBB0_2283
